# k20: k16 + nt hint on the 32 in-proj epilogue global stores (plain path)
# baseline (speedup 1.0000x reference)
; __device__ __forceinline__ unsigned cvt_pk_bf16(float lo, float hi) { unsigned r; asm volatile("v_cvt_pk_bf16_f32 %0, %1, %2" : "=v"(r) : "v"(lo), "v"(hi)); return r; }
;     __device__ __forceinline__ void operator()(f32x4 (&acc)[2][2][4][2], const Unit& u, int wr, int wc, int fr, int fq, LAS unsigned char*) const {
;     ...
;         const int col0 = u.pn * BM + wc * 32 + 8 * fq;
; #pragma unroll
;         for (int ai = 0; ai < 2; ++ai)
; #pragma unroll
;             for (int m = 0; m < 4; ++m) { bf16_t* rowp = O + (size_t)(row0 + ai * HALF + m * 16) * ldc + col0;
; #pragma unroll
;                 for (int bj = 0; bj < 2; ++bj) { const f32x4 v0 = acc[ai][bj][m][0], v1 = acc[ai][bj][m][1];
;                     u32x4 w; w.x = cvt_pk_bf16(v0[0], v0[1]); w.y = cvt_pk_bf16(v0[2], v0[3]); w.z = cvt_pk_bf16(v1[0], v1[1]); w.w = cvt_pk_bf16(v1[2], v1[3]);
;                     *(u32x4*)(rowp + bj * HALF) = w; } }
.LBB0_78:
	v_mad_i64_i32 v[146:147], s[26:27], v144, s14, 0
	v_lshl_add_u64 v[146:147], v[146:147], 1, s[4:5]
	v_lshl_or_b32 v176, s23, 9, v152
	v_lshl_add_u64 v[146:147], v[146:147], 0, v[176:177]
	v_cvt_pk_bf16_f32 v160, v124, v125
	v_cvt_pk_bf16_f32 v161, v126, v127
	v_cvt_pk_bf16_f32 v162, v120, v121
	v_cvt_pk_bf16_f32 v163, v122, v123
	global_store_dwordx4 v[146:147], v[160:163], off nt
	s_nop 1
	v_cvt_pk_bf16_f32 v160, v116, v117
	v_cvt_pk_bf16_f32 v161, v118, v119
	v_cvt_pk_bf16_f32 v162, v112, v113
	v_cvt_pk_bf16_f32 v163, v114, v115
	global_store_dwordx4 v[146:147], v[160:163], off offset:256 nt
	v_mad_i64_i32 v[146:147], s[26:27], v159, s14, 0
	v_lshl_add_u64 v[146:147], v[146:147], 1, s[4:5]
	v_lshl_add_u64 v[146:147], v[146:147], 0, v[176:177]
	v_cvt_pk_bf16_f32 v160, v108, v109
	v_cvt_pk_bf16_f32 v161, v110, v111
	v_cvt_pk_bf16_f32 v162, v104, v105
	v_cvt_pk_bf16_f32 v163, v106, v107
	global_store_dwordx4 v[146:147], v[160:163], off nt
	s_nop 1
	v_cvt_pk_bf16_f32 v160, v100, v101
	v_cvt_pk_bf16_f32 v161, v102, v103
	v_cvt_pk_bf16_f32 v162, v96, v97
	v_cvt_pk_bf16_f32 v163, v98, v99
	global_store_dwordx4 v[146:147], v[160:163], off offset:256 nt
	v_mad_i64_i32 v[146:147], s[26:27], v158, s14, 0
	v_lshl_add_u64 v[146:147], v[146:147], 1, s[4:5]
	v_lshl_add_u64 v[146:147], v[146:147], 0, v[176:177]
	v_cvt_pk_bf16_f32 v160, v92, v93
	v_cvt_pk_bf16_f32 v161, v94, v95
	v_cvt_pk_bf16_f32 v162, v88, v89
	v_cvt_pk_bf16_f32 v163, v90, v91
	global_store_dwordx4 v[146:147], v[160:163], off nt
	s_nop 1
	v_cvt_pk_bf16_f32 v160, v84, v85
	v_cvt_pk_bf16_f32 v161, v86, v87
	v_cvt_pk_bf16_f32 v162, v80, v81
	v_cvt_pk_bf16_f32 v163, v82, v83
	global_store_dwordx4 v[146:147], v[160:163], off offset:256 nt
	v_mad_i64_i32 v[146:147], s[26:27], v157, s14, 0
	v_lshl_add_u64 v[146:147], v[146:147], 1, s[4:5]
	v_lshl_add_u64 v[146:147], v[146:147], 0, v[176:177]
	v_cvt_pk_bf16_f32 v160, v76, v77
	v_cvt_pk_bf16_f32 v161, v78, v79
	v_cvt_pk_bf16_f32 v162, v72, v73
	v_cvt_pk_bf16_f32 v163, v74, v75
	global_store_dwordx4 v[146:147], v[160:163], off nt
	s_nop 1
	v_cvt_pk_bf16_f32 v160, v68, v69
	v_cvt_pk_bf16_f32 v161, v70, v71
	v_cvt_pk_bf16_f32 v162, v64, v65
	v_cvt_pk_bf16_f32 v163, v66, v67
	global_store_dwordx4 v[146:147], v[160:163], off offset:256 nt
	v_mad_i64_i32 v[146:147], s[26:27], v156, s14, 0
	v_lshl_add_u64 v[146:147], v[146:147], 1, s[4:5]
	v_lshl_add_u64 v[146:147], v[146:147], 0, v[176:177]
	v_cvt_pk_bf16_f32 v160, v60, v61
	v_cvt_pk_bf16_f32 v161, v62, v63
	v_cvt_pk_bf16_f32 v162, v56, v57
	v_cvt_pk_bf16_f32 v163, v58, v59
	global_store_dwordx4 v[146:147], v[160:163], off nt
	s_nop 1
	v_cvt_pk_bf16_f32 v160, v52, v53
	v_cvt_pk_bf16_f32 v161, v54, v55
	v_cvt_pk_bf16_f32 v162, v48, v49
	v_cvt_pk_bf16_f32 v163, v50, v51
	global_store_dwordx4 v[146:147], v[160:163], off offset:256 nt
	v_mad_i64_i32 v[146:147], s[26:27], v155, s14, 0
	v_lshl_add_u64 v[146:147], v[146:147], 1, s[4:5]
	v_lshl_add_u64 v[146:147], v[146:147], 0, v[176:177]
	v_cvt_pk_bf16_f32 v160, v44, v45
	v_cvt_pk_bf16_f32 v161, v46, v47
	v_cvt_pk_bf16_f32 v162, v40, v41
	v_cvt_pk_bf16_f32 v163, v42, v43
	global_store_dwordx4 v[146:147], v[160:163], off nt
	s_nop 1
	v_cvt_pk_bf16_f32 v160, v36, v37
	v_cvt_pk_bf16_f32 v161, v38, v39
	v_cvt_pk_bf16_f32 v162, v32, v33
	v_cvt_pk_bf16_f32 v163, v34, v35
	global_store_dwordx4 v[146:147], v[160:163], off offset:256 nt
	v_mad_i64_i32 v[146:147], s[26:27], v154, s14, 0
	v_lshl_add_u64 v[146:147], v[146:147], 1, s[4:5]
	v_lshl_add_u64 v[146:147], v[146:147], 0, v[176:177]
	v_cvt_pk_bf16_f32 v160, v28, v29
	v_cvt_pk_bf16_f32 v161, v30, v31
	v_cvt_pk_bf16_f32 v162, v24, v25
	v_cvt_pk_bf16_f32 v163, v26, v27
	global_store_dwordx4 v[146:147], v[160:163], off nt
	s_nop 1
	v_cvt_pk_bf16_f32 v160, v20, v21
	v_cvt_pk_bf16_f32 v161, v22, v23
	v_cvt_pk_bf16_f32 v162, v16, v17
	v_cvt_pk_bf16_f32 v163, v18, v19
	global_store_dwordx4 v[146:147], v[160:163], off offset:256 nt
	v_mad_i64_i32 v[146:147], s[26:27], v153, s14, 0
	v_lshl_add_u64 v[146:147], v[146:147], 1, s[4:5]
	v_lshl_add_u64 v[146:147], v[146:147], 0, v[176:177]
	v_cvt_pk_bf16_f32 v160, v12, v13
	v_cvt_pk_bf16_f32 v161, v14, v15
	v_cvt_pk_bf16_f32 v162, v8, v9
	v_cvt_pk_bf16_f32 v163, v10, v11
	global_store_dwordx4 v[146:147], v[160:163], off nt
	s_nop 1
	v_cvt_pk_bf16_f32 v160, v4, v5
	v_cvt_pk_bf16_f32 v161, v6, v7
	v_cvt_pk_bf16_f32 v162, v0, v1
	v_cvt_pk_bf16_f32 v163, v2, v3
	global_store_dwordx4 v[146:147], v[160:163], off offset:256 nt
	s_cbranch_execnz .LBB0_77
; __device__ __forceinline__ unsigned cvt_pk_bf16(float lo, float hi) { unsigned r; asm volatile("v_cvt_pk_bf16_f32 %0, %1, %2" : "=v"(r) : "v"(lo), "v"(hi)); return r; }
;     __device__ __forceinline__ void operator()(f32x4 (&acc)[2][2][4][2], const Unit& u, int wr, int wc, int fr, int fq, LAS unsigned char*) const {
;         const int row0 = u.pm * BM + wr * 64 + fr;
;         if (u.pn < rope_tiles) {
;             const float sc = u.pn >= 8 ? 0.0625f : 1.f;
;             const int i0 = (wc & 1) * 32 + fq * 8; const int colb = u.pn * BM + (wc >> 1) * 128 + (wc & 1) * 32 + fq * 8;
; #pragma unroll
;             for (int ai = 0; ai < 2; ++ai)
; #pragma unroll
;                 for (int m = 0; m < 4; ++m) { const int row = row0 + ai * HALF + m * 16; const int t = row & (SEQ - 1); const int pos = (wc >> 1) ? (t & 63) : (t >> 6);
;                     const f32x4 c0 = *(const f32x4*)(cosT + pos * 64 + i0), c1 = *(const f32x4*)(cosT + pos * 64 + i0 + 4), s0 = *(const f32x4*)(sinT + pos * 64 + i0), s1 = *(const f32x4*)(sinT + pos * 64 + i0 + 4);
;                     const f32x4 x0 = acc[ai][0][m][0], x1 = acc[ai][0][m][1], y0 = acc[ai][1][m][0], y1 = acc[ai][1][m][1];
;                     const f32x4 xa0 = (x0 * c0 - y0 * s0) * sc, xa1 = (x1 * c1 - y1 * s1) * sc, yb0 = (y0 * c0 + x0 * s0) * sc, yb1 = (y1 * c1 + x1 * s1) * sc;
;                     bf16_t* rowp = O + (size_t)row * ldc + colb;
;                     u32x4 w; w.x = cvt_pk_bf16(xa0[0], xa0[1]); w.y = cvt_pk_bf16(xa0[2], xa0[3]); w.z = cvt_pk_bf16(xa1[0], xa1[1]); w.w = cvt_pk_bf16(xa1[2], xa1[3]);
;                     *(u32x4*)(rowp) = w;
;                     w.x = cvt_pk_bf16(yb0[0], yb0[1]); w.y = cvt_pk_bf16(yb0[2], yb0[3]); w.z = cvt_pk_bf16(yb1[0], yb1[1]); w.w = cvt_pk_bf16(yb1[2], yb1[3]);
;                     *(u32x4*)(rowp + 64) = w;
;                     if (m & 1) asm volatile("" ::: "memory"); }
.LBB0_79:
	v_mov_b32_e32 v190, s24
	v_cndmask_b32_e64 v146, v148, v190, s[36:37]
	v_and_b32_e32 v146, 0xfc0, v146
	v_lshlrev_b32_e32 v176, 2, v146
	v_lshl_add_u64 v[146:147], v[138:139], 0, v[176:177]
	global_load_dwordx4 v[160:163], v[146:147], off
	global_load_dwordx4 v[164:167], v[146:147], off offset:16
	v_lshl_add_u64 v[146:147], v[136:137], 0, v[176:177]
	global_load_dwordx4 v[168:171], v[146:147], off
	global_load_dwordx4 v[172:175], v[146:147], off offset:16
	s_cmp_gt_i32 s23, 7
	v_lshl_or_b32 v146, s23, 8, v150
	v_lshlrev_b32_e32 v176, 6, v159
	v_mad_i64_i32 v[178:179], s[24:25], v144, s14, 0
	s_cselect_b64 vcc, -1, 0
	v_mov_b32_e32 v144, 0x3d800000
	v_ashrrev_i32_e32 v147, 31, v146
	v_cndmask_b32_e64 v176, v176, v190, s[36:37]
	v_cndmask_b32_e32 v144, 1.0, v144, vcc
	v_lshl_add_u64 v[178:179], v[178:179], 1, s[4:5]
	v_lshlrev_b64 v[146:147], 1, v[146:147]
	v_and_b32_e32 v176, 0xfc0, v176
	v_lshl_add_u64 v[178:179], v[178:179], 0, v[146:147]
	v_lshlrev_b32_e32 v176, 2, v176
	v_lshl_add_u64 v[180:181], v[138:139], 0, v[176:177]
	s_waitcnt vmcnt(0)
	v_pk_mul_f32 v[182:183], v[118:119], v[162:163]
	v_pk_mul_f32 v[184:185], v[116:117], v[160:161]
	v_pk_mul_f32 v[186:187], v[114:115], v[166:167]
	v_pk_mul_f32 v[188:189], v[112:113], v[164:165]
	v_pk_mul_f32 v[166:167], v[122:123], v[166:167]
	v_pk_mul_f32 v[164:165], v[120:121], v[164:165]
	v_pk_mul_f32 v[162:163], v[126:127], v[162:163]
	v_pk_mul_f32 v[160:161], v[124:125], v[160:161]
	v_pk_fma_f32 v[126:127], v[126:127], v[170:171], v[182:183] neg_lo:[0,0,1] neg_hi:[0,0,1]
	v_pk_fma_f32 v[124:125], v[124:125], v[168:169], v[184:185] neg_lo:[0,0,1] neg_hi:[0,0,1]
	v_pk_fma_f32 v[122:123], v[122:123], v[174:175], v[186:187] neg_lo:[0,0,1] neg_hi:[0,0,1]
	v_pk_fma_f32 v[120:121], v[120:121], v[172:173], v[188:189] neg_lo:[0,0,1] neg_hi:[0,0,1]
	v_pk_fma_f32 v[114:115], v[114:115], v[174:175], v[166:167]
	v_pk_fma_f32 v[112:113], v[112:113], v[172:173], v[164:165]
	v_pk_fma_f32 v[118:119], v[118:119], v[170:171], v[162:163]
	v_pk_fma_f32 v[116:117], v[116:117], v[168:169], v[160:161]
	v_pk_mul_f32 v[126:127], v[144:145], v[126:127] op_sel_hi:[0,1]
	v_pk_mul_f32 v[124:125], v[144:145], v[124:125] op_sel_hi:[0,1]
	v_pk_mul_f32 v[122:123], v[144:145], v[122:123] op_sel_hi:[0,1]
	v_pk_mul_f32 v[120:121], v[144:145], v[120:121] op_sel_hi:[0,1]
	v_pk_mul_f32 v[160:161], v[144:145], v[114:115] op_sel_hi:[0,1]
	v_pk_mul_f32 v[162:163], v[144:145], v[112:113] op_sel_hi:[0,1]
	v_cvt_pk_bf16_f32 v112, v124, v125
	v_cvt_pk_bf16_f32 v113, v126, v127
	v_cvt_pk_bf16_f32 v114, v120, v121
	v_cvt_pk_bf16_f32 v115, v122, v123
	v_pk_mul_f32 v[118:119], v[144:145], v[118:119] op_sel_hi:[0,1]
	v_pk_mul_f32 v[116:117], v[144:145], v[116:117] op_sel_hi:[0,1]
	global_store_dwordx4 v[178:179], v[112:115], off nt
	v_lshl_add_u64 v[124:125], v[136:137], 0, v[176:177]
	s_nop 0
	v_cvt_pk_bf16_f32 v112, v116, v117
	v_cvt_pk_bf16_f32 v113, v118, v119
	v_cvt_pk_bf16_f32 v114, v162, v163
	v_cvt_pk_bf16_f32 v115, v160, v161
	global_store_dwordx4 v[178:179], v[112:115], off offset:128 nt
	global_load_dwordx4 v[112:115], v[180:181], off
	s_nop 0
	global_load_dwordx4 v[116:119], v[180:181], off offset:16
	global_load_dwordx4 v[120:123], v[124:125], off
	s_nop 0
	global_load_dwordx4 v[124:127], v[124:125], off offset:16
	v_mad_i64_i32 v[160:161], s[24:25], v159, s14, 0
	v_lshlrev_b32_e32 v159, 6, v158
	v_lshl_add_u64 v[160:161], v[160:161], 1, s[4:5]
	v_cndmask_b32_e64 v159, v159, v190, s[36:37]
	v_and_b32_e32 v159, 0xfc0, v159
	v_lshl_add_u64 v[160:161], v[160:161], 0, v[146:147]
	v_lshlrev_b32_e32 v176, 2, v159
	v_lshl_add_u64 v[162:163], v[138:139], 0, v[176:177]
	s_waitcnt vmcnt(3)
	v_pk_mul_f32 v[164:165], v[102:103], v[114:115]
	v_pk_mul_f32 v[166:167], v[100:101], v[112:113]
	s_waitcnt vmcnt(2)
	v_pk_mul_f32 v[168:169], v[98:99], v[118:119]
	v_pk_mul_f32 v[170:171], v[96:97], v[116:117]
	v_pk_mul_f32 v[118:119], v[106:107], v[118:119]
	v_pk_mul_f32 v[116:117], v[104:105], v[116:117]
	v_pk_mul_f32 v[114:115], v[110:111], v[114:115]
	v_pk_mul_f32 v[112:113], v[108:109], v[112:113]
	s_waitcnt vmcnt(1)
	v_pk_fma_f32 v[110:111], v[110:111], v[122:123], v[164:165] neg_lo:[0,0,1] neg_hi:[0,0,1]
	v_pk_fma_f32 v[108:109], v[108:109], v[120:121], v[166:167] neg_lo:[0,0,1] neg_hi:[0,0,1]
	s_waitcnt vmcnt(0)
	v_pk_fma_f32 v[106:107], v[106:107], v[126:127], v[168:169] neg_lo:[0,0,1] neg_hi:[0,0,1]
	v_pk_fma_f32 v[104:105], v[104:105], v[124:125], v[170:171] neg_lo:[0,0,1] neg_hi:[0,0,1]
	v_pk_fma_f32 v[98:99], v[98:99], v[126:127], v[118:119]
	v_pk_fma_f32 v[96:97], v[96:97], v[124:125], v[116:117]
	v_pk_fma_f32 v[102:103], v[102:103], v[122:123], v[114:115]
	v_pk_fma_f32 v[100:101], v[100:101], v[120:121], v[112:113]
	v_pk_mul_f32 v[110:111], v[144:145], v[110:111] op_sel_hi:[0,1]
	v_pk_mul_f32 v[108:109], v[144:145], v[108:109] op_sel_hi:[0,1]
	v_pk_mul_f32 v[106:107], v[144:145], v[106:107] op_sel_hi:[0,1]
	v_pk_mul_f32 v[104:105], v[144:145], v[104:105] op_sel_hi:[0,1]
	v_pk_mul_f32 v[112:113], v[144:145], v[98:99] op_sel_hi:[0,1]
	v_pk_mul_f32 v[114:115], v[144:145], v[96:97] op_sel_hi:[0,1]
	v_cvt_pk_bf16_f32 v96, v108, v109
	v_cvt_pk_bf16_f32 v97, v110, v111
	v_cvt_pk_bf16_f32 v98, v104, v105
	v_cvt_pk_bf16_f32 v99, v106, v107
	v_pk_mul_f32 v[102:103], v[144:145], v[102:103] op_sel_hi:[0,1]
	v_pk_mul_f32 v[100:101], v[144:145], v[100:101] op_sel_hi:[0,1]
	global_store_dwordx4 v[160:161], v[96:99], off nt
	v_lshl_add_u64 v[108:109], v[136:137], 0, v[176:177]
	s_nop 0
	v_cvt_pk_bf16_f32 v96, v100, v101
	v_cvt_pk_bf16_f32 v97, v102, v103
	v_cvt_pk_bf16_f32 v98, v114, v115
	v_cvt_pk_bf16_f32 v99, v112, v113
	global_store_dwordx4 v[160:161], v[96:99], off offset:128 nt
	global_load_dwordx4 v[96:99], v[162:163], off
	global_load_dwordx4 v[100:103], v[162:163], off offset:16
	global_load_dwordx4 v[104:107], v[108:109], off
	s_nop 0
	global_load_dwordx4 v[108:111], v[108:109], off offset:16
	v_lshlrev_b32_e32 v114, 6, v157
	v_mad_i64_i32 v[112:113], s[24:25], v158, s14, 0
	v_cndmask_b32_e64 v114, v114, v190, s[36:37]
	v_lshl_add_u64 v[112:113], v[112:113], 1, s[4:5]
	v_and_b32_e32 v114, 0xfc0, v114
	v_lshl_add_u64 v[112:113], v[112:113], 0, v[146:147]
	v_lshlrev_b32_e32 v176, 2, v114
	v_lshl_add_u64 v[114:115], v[138:139], 0, v[176:177]
	s_waitcnt vmcnt(3)
; __device__ __forceinline__ unsigned cvt_pk_bf16(float lo, float hi) { unsigned r; asm volatile("v_cvt_pk_bf16_f32 %0, %1, %2" : "=v"(r) : "v"(lo), "v"(hi)); return r; }
;     __device__ __forceinline__ void operator()(f32x4 (&acc)[2][2][4][2], const Unit& u, int wr, int wc, int fr, int fq, LAS unsigned char*) const {
;     ...
;                 for (int m = 0; m < 4; ++m) { const int row = row0 + ai * HALF + m * 16; const int t = row & (SEQ - 1); const int pos = (wc >> 1) ? (t & 63) : (t >> 6);
;                     const f32x4 c0 = *(const f32x4*)(cosT + pos * 64 + i0), c1 = *(const f32x4*)(cosT + pos * 64 + i0 + 4), s0 = *(const f32x4*)(sinT + pos * 64 + i0), s1 = *(const f32x4*)(sinT + pos * 64 + i0 + 4);
;                     const f32x4 x0 = acc[ai][0][m][0], x1 = acc[ai][0][m][1], y0 = acc[ai][1][m][0], y1 = acc[ai][1][m][1];
;                     const f32x4 xa0 = (x0 * c0 - y0 * s0) * sc, xa1 = (x1 * c1 - y1 * s1) * sc, yb0 = (y0 * c0 + x0 * s0) * sc, yb1 = (y1 * c1 + x1 * s1) * sc;
;                     bf16_t* rowp = O + (size_t)row * ldc + colb;
;                     u32x4 w; w.x = cvt_pk_bf16(xa0[0], xa0[1]); w.y = cvt_pk_bf16(xa0[2], xa0[3]); w.z = cvt_pk_bf16(xa1[0], xa1[1]); w.w = cvt_pk_bf16(xa1[2], xa1[3]);
;                     *(u32x4*)(rowp) = w;
;                     w.x = cvt_pk_bf16(yb0[0], yb0[1]); w.y = cvt_pk_bf16(yb0[2], yb0[3]); w.z = cvt_pk_bf16(yb1[0], yb1[1]); w.w = cvt_pk_bf16(yb1[2], yb1[3]);
;                     *(u32x4*)(rowp + 64) = w;
;                     if (m & 1) asm volatile("" ::: "memory"); }
	v_pk_mul_f32 v[116:117], v[86:87], v[98:99]
	v_pk_mul_f32 v[118:119], v[84:85], v[96:97]
	s_waitcnt vmcnt(2)
	v_pk_mul_f32 v[120:121], v[82:83], v[102:103]
	v_pk_mul_f32 v[122:123], v[80:81], v[100:101]
	v_pk_mul_f32 v[102:103], v[90:91], v[102:103]
	v_pk_mul_f32 v[100:101], v[88:89], v[100:101]
	v_pk_mul_f32 v[98:99], v[94:95], v[98:99]
	v_pk_mul_f32 v[96:97], v[92:93], v[96:97]
	s_waitcnt vmcnt(1)
	v_pk_fma_f32 v[94:95], v[94:95], v[106:107], v[116:117] neg_lo:[0,0,1] neg_hi:[0,0,1]
	v_pk_fma_f32 v[92:93], v[92:93], v[104:105], v[118:119] neg_lo:[0,0,1] neg_hi:[0,0,1]
	s_waitcnt vmcnt(0)
	v_pk_fma_f32 v[90:91], v[90:91], v[110:111], v[120:121] neg_lo:[0,0,1] neg_hi:[0,0,1]
	v_pk_fma_f32 v[88:89], v[88:89], v[108:109], v[122:123] neg_lo:[0,0,1] neg_hi:[0,0,1]
	v_pk_fma_f32 v[82:83], v[82:83], v[110:111], v[102:103]
	v_pk_fma_f32 v[80:81], v[80:81], v[108:109], v[100:101]
	v_pk_fma_f32 v[86:87], v[86:87], v[106:107], v[98:99]
	v_pk_fma_f32 v[84:85], v[84:85], v[104:105], v[96:97]
	v_pk_mul_f32 v[94:95], v[144:145], v[94:95] op_sel_hi:[0,1]
	v_pk_mul_f32 v[92:93], v[144:145], v[92:93] op_sel_hi:[0,1]
	v_pk_mul_f32 v[90:91], v[144:145], v[90:91] op_sel_hi:[0,1]
	v_pk_mul_f32 v[88:89], v[144:145], v[88:89] op_sel_hi:[0,1]
	v_pk_mul_f32 v[96:97], v[144:145], v[82:83] op_sel_hi:[0,1]
	v_pk_mul_f32 v[98:99], v[144:145], v[80:81] op_sel_hi:[0,1]
	v_cvt_pk_bf16_f32 v80, v92, v93
	v_cvt_pk_bf16_f32 v81, v94, v95
	v_cvt_pk_bf16_f32 v82, v88, v89
	v_cvt_pk_bf16_f32 v83, v90, v91
	v_pk_mul_f32 v[86:87], v[144:145], v[86:87] op_sel_hi:[0,1]
	v_pk_mul_f32 v[84:85], v[144:145], v[84:85] op_sel_hi:[0,1]
	global_store_dwordx4 v[112:113], v[80:83], off nt
	v_lshl_add_u64 v[92:93], v[136:137], 0, v[176:177]
	v_lshrrev_b32_e32 v108, 6, v156
	v_cvt_pk_bf16_f32 v80, v84, v85
	v_cvt_pk_bf16_f32 v81, v86, v87
	v_cvt_pk_bf16_f32 v82, v98, v99
	v_cvt_pk_bf16_f32 v83, v96, v97
	global_store_dwordx4 v[112:113], v[80:83], off offset:128 nt
	global_load_dwordx4 v[80:83], v[114:115], off
	s_nop 0
	global_load_dwordx4 v[84:87], v[114:115], off offset:16
	global_load_dwordx4 v[88:91], v[92:93], off
	s_nop 0
	global_load_dwordx4 v[92:95], v[92:93], off offset:16
	v_mad_i64_i32 v[96:97], s[24:25], v157, s14, 0
	v_lshl_add_u64 v[96:97], v[96:97], 1, s[4:5]
	v_cndmask_b32_e64 v98, v145, v108, s[36:37]
	v_lshlrev_b32_e32 v98, 8, v98
	v_lshl_add_u64 v[96:97], v[96:97], 0, v[146:147]
	v_and_b32_e32 v176, 0x3f00, v98
	v_lshl_add_u64 v[98:99], v[138:139], 0, v[176:177]
	s_waitcnt vmcnt(3)
	v_pk_mul_f32 v[100:101], v[70:71], v[82:83]
	v_pk_mul_f32 v[102:103], v[68:69], v[80:81]
	s_waitcnt vmcnt(2)
	v_pk_mul_f32 v[104:105], v[66:67], v[86:87]
	v_pk_mul_f32 v[106:107], v[64:65], v[84:85]
	v_pk_mul_f32 v[86:87], v[74:75], v[86:87]
	v_pk_mul_f32 v[84:85], v[72:73], v[84:85]
	v_pk_mul_f32 v[82:83], v[78:79], v[82:83]
	v_pk_mul_f32 v[80:81], v[76:77], v[80:81]
	s_waitcnt vmcnt(1)
	v_pk_fma_f32 v[78:79], v[78:79], v[90:91], v[100:101] neg_lo:[0,0,1] neg_hi:[0,0,1]
	v_pk_fma_f32 v[76:77], v[76:77], v[88:89], v[102:103] neg_lo:[0,0,1] neg_hi:[0,0,1]
	s_waitcnt vmcnt(0)
	v_pk_fma_f32 v[74:75], v[74:75], v[94:95], v[104:105] neg_lo:[0,0,1] neg_hi:[0,0,1]
	v_pk_fma_f32 v[72:73], v[72:73], v[92:93], v[106:107] neg_lo:[0,0,1] neg_hi:[0,0,1]
	v_pk_fma_f32 v[66:67], v[66:67], v[94:95], v[86:87]
	v_pk_fma_f32 v[64:65], v[64:65], v[92:93], v[84:85]
	v_pk_fma_f32 v[70:71], v[70:71], v[90:91], v[82:83]
	v_pk_fma_f32 v[68:69], v[68:69], v[88:89], v[80:81]
	v_pk_mul_f32 v[78:79], v[144:145], v[78:79] op_sel_hi:[0,1]
	v_pk_mul_f32 v[76:77], v[144:145], v[76:77] op_sel_hi:[0,1]
	v_pk_mul_f32 v[74:75], v[144:145], v[74:75] op_sel_hi:[0,1]
	v_pk_mul_f32 v[72:73], v[144:145], v[72:73] op_sel_hi:[0,1]
	v_pk_mul_f32 v[80:81], v[144:145], v[66:67] op_sel_hi:[0,1]
	v_pk_mul_f32 v[82:83], v[144:145], v[64:65] op_sel_hi:[0,1]
	v_cvt_pk_bf16_f32 v64, v76, v77
	v_cvt_pk_bf16_f32 v65, v78, v79
	v_cvt_pk_bf16_f32 v66, v72, v73
	v_cvt_pk_bf16_f32 v67, v74, v75
	v_pk_mul_f32 v[70:71], v[144:145], v[70:71] op_sel_hi:[0,1]
	v_pk_mul_f32 v[68:69], v[144:145], v[68:69] op_sel_hi:[0,1]
	global_store_dwordx4 v[96:97], v[64:67], off nt
	v_lshl_add_u64 v[76:77], v[136:137], 0, v[176:177]
	s_nop 0
	v_cvt_pk_bf16_f32 v64, v68, v69
	v_cvt_pk_bf16_f32 v65, v70, v71
	v_cvt_pk_bf16_f32 v66, v82, v83
	v_cvt_pk_bf16_f32 v67, v80, v81
	global_store_dwordx4 v[96:97], v[64:67], off offset:128 nt
	global_load_dwordx4 v[64:67], v[98:99], off
	global_load_dwordx4 v[68:71], v[98:99], off offset:16
	global_load_dwordx4 v[72:75], v[76:77], off
	s_nop 0
	global_load_dwordx4 v[76:79], v[76:77], off offset:16
	v_mad_i64_i32 v[80:81], s[24:25], v156, s14, 0
	v_cndmask_b32_e64 v82, v155, v108, s[36:37]
	v_lshl_add_u64 v[80:81], v[80:81], 1, s[4:5]
	v_lshlrev_b32_e32 v82, 8, v82
	v_lshl_add_u64 v[80:81], v[80:81], 0, v[146:147]
	v_and_b32_e32 v176, 0x3f00, v82
	v_lshl_add_u64 v[82:83], v[138:139], 0, v[176:177]
	s_waitcnt vmcnt(3)
	v_pk_mul_f32 v[84:85], v[54:55], v[66:67]
	v_pk_mul_f32 v[86:87], v[52:53], v[64:65]
	s_waitcnt vmcnt(2)
	v_pk_mul_f32 v[88:89], v[50:51], v[70:71]
	v_pk_mul_f32 v[90:91], v[48:49], v[68:69]
	v_pk_mul_f32 v[70:71], v[58:59], v[70:71]
	v_pk_mul_f32 v[68:69], v[56:57], v[68:69]
	v_pk_mul_f32 v[66:67], v[62:63], v[66:67]
	v_pk_mul_f32 v[64:65], v[60:61], v[64:65]
	s_waitcnt vmcnt(1)
	v_pk_fma_f32 v[62:63], v[62:63], v[74:75], v[84:85] neg_lo:[0,0,1] neg_hi:[0,0,1]
	v_pk_fma_f32 v[60:61], v[60:61], v[72:73], v[86:87] neg_lo:[0,0,1] neg_hi:[0,0,1]
	s_waitcnt vmcnt(0)
; __device__ __forceinline__ unsigned cvt_pk_bf16(float lo, float hi) { unsigned r; asm volatile("v_cvt_pk_bf16_f32 %0, %1, %2" : "=v"(r) : "v"(lo), "v"(hi)); return r; }
;     __device__ __forceinline__ void operator()(f32x4 (&acc)[2][2][4][2], const Unit& u, int wr, int wc, int fr, int fq, LAS unsigned char*) const {
;     ...
;                 for (int m = 0; m < 4; ++m) { const int row = row0 + ai * HALF + m * 16; const int t = row & (SEQ - 1); const int pos = (wc >> 1) ? (t & 63) : (t >> 6);
;                     const f32x4 c0 = *(const f32x4*)(cosT + pos * 64 + i0), c1 = *(const f32x4*)(cosT + pos * 64 + i0 + 4), s0 = *(const f32x4*)(sinT + pos * 64 + i0), s1 = *(const f32x4*)(sinT + pos * 64 + i0 + 4);
;                     const f32x4 x0 = acc[ai][0][m][0], x1 = acc[ai][0][m][1], y0 = acc[ai][1][m][0], y1 = acc[ai][1][m][1];
;                     const f32x4 xa0 = (x0 * c0 - y0 * s0) * sc, xa1 = (x1 * c1 - y1 * s1) * sc, yb0 = (y0 * c0 + x0 * s0) * sc, yb1 = (y1 * c1 + x1 * s1) * sc;
;                     bf16_t* rowp = O + (size_t)row * ldc + colb;
;                     u32x4 w; w.x = cvt_pk_bf16(xa0[0], xa0[1]); w.y = cvt_pk_bf16(xa0[2], xa0[3]); w.z = cvt_pk_bf16(xa1[0], xa1[1]); w.w = cvt_pk_bf16(xa1[2], xa1[3]);
;                     *(u32x4*)(rowp) = w;
;                     w.x = cvt_pk_bf16(yb0[0], yb0[1]); w.y = cvt_pk_bf16(yb0[2], yb0[3]); w.z = cvt_pk_bf16(yb1[0], yb1[1]); w.w = cvt_pk_bf16(yb1[2], yb1[3]);
;                     *(u32x4*)(rowp + 64) = w;
;                     if (m & 1) asm volatile("" ::: "memory"); }
	v_pk_fma_f32 v[58:59], v[58:59], v[78:79], v[88:89] neg_lo:[0,0,1] neg_hi:[0,0,1]
	v_pk_fma_f32 v[56:57], v[56:57], v[76:77], v[90:91] neg_lo:[0,0,1] neg_hi:[0,0,1]
	v_pk_fma_f32 v[50:51], v[50:51], v[78:79], v[70:71]
	v_pk_fma_f32 v[48:49], v[48:49], v[76:77], v[68:69]
	v_pk_fma_f32 v[54:55], v[54:55], v[74:75], v[66:67]
	v_pk_fma_f32 v[52:53], v[52:53], v[72:73], v[64:65]
	v_pk_mul_f32 v[62:63], v[144:145], v[62:63] op_sel_hi:[0,1]
	v_pk_mul_f32 v[60:61], v[144:145], v[60:61] op_sel_hi:[0,1]
	v_pk_mul_f32 v[58:59], v[144:145], v[58:59] op_sel_hi:[0,1]
	v_pk_mul_f32 v[56:57], v[144:145], v[56:57] op_sel_hi:[0,1]
	v_pk_mul_f32 v[64:65], v[144:145], v[50:51] op_sel_hi:[0,1]
	v_pk_mul_f32 v[66:67], v[144:145], v[48:49] op_sel_hi:[0,1]
	v_cvt_pk_bf16_f32 v48, v60, v61
	v_cvt_pk_bf16_f32 v49, v62, v63
	v_cvt_pk_bf16_f32 v50, v56, v57
	v_cvt_pk_bf16_f32 v51, v58, v59
	v_pk_mul_f32 v[54:55], v[144:145], v[54:55] op_sel_hi:[0,1]
	v_pk_mul_f32 v[52:53], v[144:145], v[52:53] op_sel_hi:[0,1]
	global_store_dwordx4 v[80:81], v[48:51], off nt
	v_lshl_add_u64 v[60:61], v[136:137], 0, v[176:177]
	s_nop 0
	v_cvt_pk_bf16_f32 v48, v52, v53
	v_cvt_pk_bf16_f32 v49, v54, v55
	v_cvt_pk_bf16_f32 v50, v66, v67
	v_cvt_pk_bf16_f32 v51, v64, v65
	global_store_dwordx4 v[80:81], v[48:51], off offset:128 nt
	global_load_dwordx4 v[48:51], v[82:83], off
	s_nop 0
	global_load_dwordx4 v[52:55], v[82:83], off offset:16
	global_load_dwordx4 v[56:59], v[60:61], off
	s_nop 0
	global_load_dwordx4 v[60:63], v[60:61], off offset:16
	v_mad_i64_i32 v[64:65], s[24:25], v155, s14, 0
	v_lshl_add_u64 v[64:65], v[64:65], 1, s[4:5]
	v_cndmask_b32_e64 v66, v154, v108, s[36:37]
	v_lshlrev_b32_e32 v66, 8, v66
	v_lshl_add_u64 v[64:65], v[64:65], 0, v[146:147]
	v_and_b32_e32 v176, 0x3f00, v66
	v_lshl_add_u64 v[66:67], v[138:139], 0, v[176:177]
	s_waitcnt vmcnt(3)
	v_pk_mul_f32 v[68:69], v[38:39], v[50:51]
	v_pk_mul_f32 v[70:71], v[36:37], v[48:49]
	s_waitcnt vmcnt(2)
	v_pk_mul_f32 v[72:73], v[34:35], v[54:55]
	v_pk_mul_f32 v[74:75], v[32:33], v[52:53]
	v_pk_mul_f32 v[54:55], v[42:43], v[54:55]
	v_pk_mul_f32 v[52:53], v[40:41], v[52:53]
	v_pk_mul_f32 v[50:51], v[46:47], v[50:51]
	v_pk_mul_f32 v[48:49], v[44:45], v[48:49]
	s_waitcnt vmcnt(1)
	v_pk_fma_f32 v[46:47], v[46:47], v[58:59], v[68:69] neg_lo:[0,0,1] neg_hi:[0,0,1]
	v_pk_fma_f32 v[44:45], v[44:45], v[56:57], v[70:71] neg_lo:[0,0,1] neg_hi:[0,0,1]
	s_waitcnt vmcnt(0)
	v_pk_fma_f32 v[42:43], v[42:43], v[62:63], v[72:73] neg_lo:[0,0,1] neg_hi:[0,0,1]
	v_pk_fma_f32 v[40:41], v[40:41], v[60:61], v[74:75] neg_lo:[0,0,1] neg_hi:[0,0,1]
	v_pk_fma_f32 v[34:35], v[34:35], v[62:63], v[54:55]
	v_pk_fma_f32 v[32:33], v[32:33], v[60:61], v[52:53]
	v_pk_fma_f32 v[38:39], v[38:39], v[58:59], v[50:51]
	v_pk_fma_f32 v[36:37], v[36:37], v[56:57], v[48:49]
	v_pk_mul_f32 v[46:47], v[144:145], v[46:47] op_sel_hi:[0,1]
	v_pk_mul_f32 v[44:45], v[144:145], v[44:45] op_sel_hi:[0,1]
	v_pk_mul_f32 v[42:43], v[144:145], v[42:43] op_sel_hi:[0,1]
	v_pk_mul_f32 v[40:41], v[144:145], v[40:41] op_sel_hi:[0,1]
	v_pk_mul_f32 v[48:49], v[144:145], v[34:35] op_sel_hi:[0,1]
	v_pk_mul_f32 v[50:51], v[144:145], v[32:33] op_sel_hi:[0,1]
	v_cvt_pk_bf16_f32 v32, v44, v45
	v_cvt_pk_bf16_f32 v33, v46, v47
	v_cvt_pk_bf16_f32 v34, v40, v41
	v_cvt_pk_bf16_f32 v35, v42, v43
	v_pk_mul_f32 v[38:39], v[144:145], v[38:39] op_sel_hi:[0,1]
	v_pk_mul_f32 v[36:37], v[144:145], v[36:37] op_sel_hi:[0,1]
	global_store_dwordx4 v[64:65], v[32:35], off nt
	v_lshl_add_u64 v[44:45], v[136:137], 0, v[176:177]
	s_nop 0
	v_cvt_pk_bf16_f32 v32, v36, v37
	v_cvt_pk_bf16_f32 v33, v38, v39
	v_cvt_pk_bf16_f32 v34, v50, v51
	v_cvt_pk_bf16_f32 v35, v48, v49
	global_store_dwordx4 v[64:65], v[32:35], off offset:128 nt
	global_load_dwordx4 v[32:35], v[66:67], off
	global_load_dwordx4 v[36:39], v[66:67], off offset:16
	global_load_dwordx4 v[40:43], v[44:45], off
	s_nop 0
	global_load_dwordx4 v[44:47], v[44:45], off offset:16
	v_mad_i64_i32 v[48:49], s[24:25], v154, s14, 0
	v_cndmask_b32_e64 v50, v153, v108, s[36:37]
	v_lshl_add_u64 v[48:49], v[48:49], 1, s[4:5]
	v_lshlrev_b32_e32 v50, 8, v50
	v_lshl_add_u64 v[48:49], v[48:49], 0, v[146:147]
	v_and_b32_e32 v176, 0x3f00, v50
	v_lshl_add_u64 v[50:51], v[138:139], 0, v[176:177]
	s_waitcnt vmcnt(3)
; __device__ __forceinline__ unsigned cvt_pk_bf16(float lo, float hi) { unsigned r; asm volatile("v_cvt_pk_bf16_f32 %0, %1, %2" : "=v"(r) : "v"(lo), "v"(hi)); return r; }
;     __device__ __forceinline__ void operator()(f32x4 (&acc)[2][2][4][2], const Unit& u, int wr, int wc, int fr, int fq, LAS unsigned char*) const {
;     ...
;                 for (int m = 0; m < 4; ++m) { const int row = row0 + ai * HALF + m * 16; const int t = row & (SEQ - 1); const int pos = (wc >> 1) ? (t & 63) : (t >> 6);
;                     const f32x4 c0 = *(const f32x4*)(cosT + pos * 64 + i0), c1 = *(const f32x4*)(cosT + pos * 64 + i0 + 4), s0 = *(const f32x4*)(sinT + pos * 64 + i0), s1 = *(const f32x4*)(sinT + pos * 64 + i0 + 4);
;                     const f32x4 x0 = acc[ai][0][m][0], x1 = acc[ai][0][m][1], y0 = acc[ai][1][m][0], y1 = acc[ai][1][m][1];
;                     const f32x4 xa0 = (x0 * c0 - y0 * s0) * sc, xa1 = (x1 * c1 - y1 * s1) * sc, yb0 = (y0 * c0 + x0 * s0) * sc, yb1 = (y1 * c1 + x1 * s1) * sc;
;                     bf16_t* rowp = O + (size_t)row * ldc + colb;
;                     u32x4 w; w.x = cvt_pk_bf16(xa0[0], xa0[1]); w.y = cvt_pk_bf16(xa0[2], xa0[3]); w.z = cvt_pk_bf16(xa1[0], xa1[1]); w.w = cvt_pk_bf16(xa1[2], xa1[3]);
;                     *(u32x4*)(rowp) = w;
;                     w.x = cvt_pk_bf16(yb0[0], yb0[1]); w.y = cvt_pk_bf16(yb0[2], yb0[3]); w.z = cvt_pk_bf16(yb1[0], yb1[1]); w.w = cvt_pk_bf16(yb1[2], yb1[3]);
;                     *(u32x4*)(rowp + 64) = w;
;                     if (m & 1) asm volatile("" ::: "memory"); }
;             return;
	v_pk_mul_f32 v[52:53], v[22:23], v[34:35]
	v_pk_mul_f32 v[54:55], v[20:21], v[32:33]
	s_waitcnt vmcnt(2)
	v_pk_mul_f32 v[56:57], v[18:19], v[38:39]
	v_pk_mul_f32 v[58:59], v[16:17], v[36:37]
	v_pk_mul_f32 v[38:39], v[26:27], v[38:39]
	v_pk_mul_f32 v[36:37], v[24:25], v[36:37]
	v_pk_mul_f32 v[34:35], v[30:31], v[34:35]
	v_pk_mul_f32 v[32:33], v[28:29], v[32:33]
	s_waitcnt vmcnt(1)
	v_pk_fma_f32 v[30:31], v[30:31], v[42:43], v[52:53] neg_lo:[0,0,1] neg_hi:[0,0,1]
	v_pk_fma_f32 v[28:29], v[28:29], v[40:41], v[54:55] neg_lo:[0,0,1] neg_hi:[0,0,1]
	s_waitcnt vmcnt(0)
	v_pk_fma_f32 v[26:27], v[26:27], v[46:47], v[56:57] neg_lo:[0,0,1] neg_hi:[0,0,1]
	v_pk_fma_f32 v[24:25], v[24:25], v[44:45], v[58:59] neg_lo:[0,0,1] neg_hi:[0,0,1]
	v_pk_fma_f32 v[18:19], v[18:19], v[46:47], v[38:39]
	v_pk_fma_f32 v[16:17], v[16:17], v[44:45], v[36:37]
	v_pk_fma_f32 v[22:23], v[22:23], v[42:43], v[34:35]
	v_pk_fma_f32 v[20:21], v[20:21], v[40:41], v[32:33]
	v_pk_mul_f32 v[30:31], v[144:145], v[30:31] op_sel_hi:[0,1]
	v_pk_mul_f32 v[28:29], v[144:145], v[28:29] op_sel_hi:[0,1]
	v_pk_mul_f32 v[26:27], v[144:145], v[26:27] op_sel_hi:[0,1]
	v_pk_mul_f32 v[24:25], v[144:145], v[24:25] op_sel_hi:[0,1]
	v_pk_mul_f32 v[32:33], v[144:145], v[18:19] op_sel_hi:[0,1]
	v_pk_mul_f32 v[34:35], v[144:145], v[16:17] op_sel_hi:[0,1]
	v_cvt_pk_bf16_f32 v16, v28, v29
	v_cvt_pk_bf16_f32 v17, v30, v31
	v_cvt_pk_bf16_f32 v18, v24, v25
	v_cvt_pk_bf16_f32 v19, v26, v27
	v_pk_mul_f32 v[22:23], v[144:145], v[22:23] op_sel_hi:[0,1]
	v_pk_mul_f32 v[20:21], v[144:145], v[20:21] op_sel_hi:[0,1]
	global_store_dwordx4 v[48:49], v[16:19], off nt
	v_lshl_add_u64 v[28:29], v[136:137], 0, v[176:177]
	s_nop 0
	v_cvt_pk_bf16_f32 v16, v20, v21
	v_cvt_pk_bf16_f32 v17, v22, v23
	v_cvt_pk_bf16_f32 v18, v34, v35
	v_cvt_pk_bf16_f32 v19, v32, v33
	global_store_dwordx4 v[48:49], v[16:19], off offset:128 nt
	global_load_dwordx4 v[16:19], v[50:51], off
	s_nop 0
	global_load_dwordx4 v[20:23], v[50:51], off offset:16
	global_load_dwordx4 v[24:27], v[28:29], off
	s_nop 0
	global_load_dwordx4 v[28:31], v[28:29], off offset:16
	v_mad_i64_i32 v[32:33], s[24:25], v153, s14, 0
	v_lshl_add_u64 v[32:33], v[32:33], 1, s[4:5]
	v_lshl_add_u64 v[32:33], v[32:33], 0, v[146:147]
	s_waitcnt vmcnt(3)
	v_pk_mul_f32 v[34:35], v[6:7], v[18:19]
	v_pk_mul_f32 v[36:37], v[4:5], v[16:17]
	s_waitcnt vmcnt(2)
	v_pk_mul_f32 v[38:39], v[2:3], v[22:23]
	v_pk_mul_f32 v[40:41], v[0:1], v[20:21]
	v_pk_mul_f32 v[22:23], v[10:11], v[22:23]
	v_pk_mul_f32 v[20:21], v[8:9], v[20:21]
	v_pk_mul_f32 v[18:19], v[14:15], v[18:19]
	v_pk_mul_f32 v[16:17], v[12:13], v[16:17]
	s_waitcnt vmcnt(1)
	v_pk_fma_f32 v[14:15], v[14:15], v[26:27], v[34:35] neg_lo:[0,0,1] neg_hi:[0,0,1]
	v_pk_fma_f32 v[12:13], v[12:13], v[24:25], v[36:37] neg_lo:[0,0,1] neg_hi:[0,0,1]
	s_waitcnt vmcnt(0)
	v_pk_fma_f32 v[10:11], v[10:11], v[30:31], v[38:39] neg_lo:[0,0,1] neg_hi:[0,0,1]
	v_pk_fma_f32 v[8:9], v[8:9], v[28:29], v[40:41] neg_lo:[0,0,1] neg_hi:[0,0,1]
	v_pk_fma_f32 v[2:3], v[2:3], v[30:31], v[22:23]
	v_pk_fma_f32 v[0:1], v[0:1], v[28:29], v[20:21]
	v_pk_fma_f32 v[6:7], v[6:7], v[26:27], v[18:19]
	v_pk_fma_f32 v[4:5], v[4:5], v[24:25], v[16:17]
	v_pk_mul_f32 v[14:15], v[144:145], v[14:15] op_sel_hi:[0,1]
	v_pk_mul_f32 v[12:13], v[144:145], v[12:13] op_sel_hi:[0,1]
	v_pk_mul_f32 v[10:11], v[144:145], v[10:11] op_sel_hi:[0,1]
	v_pk_mul_f32 v[8:9], v[144:145], v[8:9] op_sel_hi:[0,1]
	v_pk_mul_f32 v[16:17], v[144:145], v[2:3] op_sel_hi:[0,1]
	v_pk_mul_f32 v[18:19], v[144:145], v[0:1] op_sel_hi:[0,1]
	v_cvt_pk_bf16_f32 v0, v12, v13
	v_cvt_pk_bf16_f32 v1, v14, v15
	v_cvt_pk_bf16_f32 v2, v8, v9
	v_cvt_pk_bf16_f32 v3, v10, v11
	v_pk_mul_f32 v[6:7], v[144:145], v[6:7] op_sel_hi:[0,1]
	v_pk_mul_f32 v[4:5], v[144:145], v[4:5] op_sel_hi:[0,1]
	global_store_dwordx4 v[32:33], v[0:3], off nt
	s_nop 1
	v_cvt_pk_bf16_f32 v0, v4, v5
	v_cvt_pk_bf16_f32 v1, v6, v7
	v_cvt_pk_bf16_f32 v2, v18, v19
	v_cvt_pk_bf16_f32 v3, v16, v17
	global_store_dwordx4 v[32:33], v[0:3], off offset:128 nt
	s_andn2_b64 vcc, exec, s[38:39]
	s_mov_b64 s[38:39], -1
	s_cbranch_vccnz .LBB0_68
